# adds: waves whose rows are fully causally masked skip the last two key tiles of an MLA unit (QK, softmax, PV), keeping DMA, barrier and running-sum bookkeeping
# speedup vs baseline: 1.0059x; 1.0008x over previous
.LBB0_1434:
	s_sub_i32 s13, s12, 0x5f
	s_cmp_ge_i32 s13, s96
	s_cbranch_scc0 .Lmla_L2_full
	v_add_f32_e32 v165, v213, v214
	v_add_f32_e32 v199, v199, v165
	s_cmp_ge_u32 s11, s10
	s_cbranch_scc1 .Lspr_k1_s
	s_add_i32 s13, s74, 0xe000
	s_mov_b32 s14, m0
	s_mov_b32 m0, s13
	s_nop 0
	global_load_lds_dwordx4 v[168:169], off
	s_mov_b32 m0, s14
.Lspr_k1_s:
	s_cmp_ge_u32 s11, s10
	s_cbranch_scc1 .Lspr_k2_s
	s_add_i32 s13, s75, 0xe000
	s_mov_b32 s14, m0
	s_mov_b32 m0, s13
	s_nop 0
	global_load_lds_dwordx4 v[170:171], off
	s_mov_b32 m0, s14
.Lspr_k2_s:
	s_cmp_ge_u32 s11, s10
	s_cbranch_scc1 .Lspr_k3_s
	s_add_i32 s13, s5, 0xe000
	s_mov_b32 s14, m0
	s_mov_b32 m0, s13
	s_nop 0
	global_load_lds_dwordx4 v[172:173], off
	s_mov_b32 m0, s14
	v_mov_b32_e32 v165, v163
	v_mov_b32_e32 v167, v163
	v_lshl_add_u64 v[168:169], v[168:169], 0, v[162:163]
	v_lshl_add_u64 v[170:171], v[170:171], 0, v[164:165]
	v_lshl_add_u64 v[172:173], v[172:173], 0, v[166:167]
.Lspr_k3_s:
	s_waitcnt lgkmcnt(0)
	s_waitcnt vmcnt(0)
	s_addk_i32 s12, 0x80
	s_add_i32 s8, s11, 2
	s_add_i32 s9, s11, 1
	v_add_u32_e32 v212, 0xffffff80, v212
	s_cmp_lt_u32 s9, s10
	s_barrier
	ds_read_b128 v[178:181], v211
	ds_read_b128 v[214:217], v211 offset:12288
	ds_read_b128 v[238:241], v210
	ds_read_b128 v[242:245], v210 offset:12288
	ds_read_b128 v[246:249], v209
	ds_read_b128 v[250:253], v209 offset:12288
	s_cbranch_scc0 .LBB0_1442
	s_mov_b32 s11, s8
	s_branch .LBB0_1425

.LBB0_1442:
	s_andn2_b64 vcc, exec, s[0:1]
	s_cbranch_vccnz .LBB0_1450
	s_lshl_b32 s0, s11, 6
	s_sub_i32 s0, s0, 32
	s_cmp_ge_i32 s0, s96
	s_cbranch_scc0 .Lmla_T_full
	s_waitcnt vmcnt(0)
	s_barrier
	s_branch .LBB0_1450
.Lmla_T_full:
	ds_read_b128 v[114:117], v211
	ds_read_b128 v[118:121], v211 offset:12288
	s_waitcnt lgkmcnt(1)
	v_mfma_f32_32x32x16_bf16 v[98:113], v[114:117], v[158:161], v[82:97]
	s_waitcnt lgkmcnt(0)
	v_mfma_f32_32x32x16_bf16 v[82:97], v[118:121], v[158:161], v[82:97]
	ds_read_b128 v[114:117], v210
	ds_read_b128 v[118:121], v210 offset:12288
	s_waitcnt lgkmcnt(1)
	v_mfma_f32_32x32x16_bf16 v[98:113], v[114:117], v[154:157], v[98:113]
	s_waitcnt lgkmcnt(0)
	v_mfma_f32_32x32x16_bf16 v[82:97], v[118:121], v[154:157], v[82:97]
	ds_read_b128 v[114:117], v209
	ds_read_b128 v[118:121], v209 offset:12288
	s_waitcnt lgkmcnt(1)
	v_mfma_f32_32x32x16_bf16 v[98:113], v[114:117], v[150:153], v[98:113]
	s_waitcnt lgkmcnt(0)
	v_mfma_f32_32x32x16_bf16 v[82:97], v[118:121], v[150:153], v[82:97]
	ds_read_b128 v[114:117], v208
	ds_read_b128 v[118:121], v208 offset:12288
	s_waitcnt lgkmcnt(1)
	v_mfma_f32_32x32x16_bf16 v[98:113], v[114:117], v[146:149], v[98:113]
	s_waitcnt lgkmcnt(0)
	v_mfma_f32_32x32x16_bf16 v[82:97], v[118:121], v[146:149], v[82:97]
	ds_read_b128 v[114:117], v207
	ds_read_b128 v[118:121], v207 offset:12288
	s_waitcnt lgkmcnt(1)
	v_mfma_f32_32x32x16_bf16 v[98:113], v[114:117], v[142:145], v[98:113]
	s_waitcnt lgkmcnt(0)
	v_mfma_f32_32x32x16_bf16 v[82:97], v[118:121], v[142:145], v[82:97]
	ds_read_b128 v[114:117], v206
	ds_read_b128 v[118:121], v206 offset:12288
	s_waitcnt lgkmcnt(1)
	v_mfma_f32_32x32x16_bf16 v[98:113], v[114:117], v[138:141], v[98:113]
	s_waitcnt lgkmcnt(0)
	v_mfma_f32_32x32x16_bf16 v[82:97], v[118:121], v[138:141], v[82:97]
	ds_read_b128 v[114:117], v205
	ds_read_b128 v[118:121], v205 offset:12288
	s_waitcnt lgkmcnt(1)
	v_mfma_f32_32x32x16_bf16 v[98:113], v[114:117], v[134:137], v[98:113]
	s_waitcnt lgkmcnt(0)
	v_mfma_f32_32x32x16_bf16 v[82:97], v[118:121], v[134:137], v[82:97]
	ds_read_b128 v[114:117], v204
	ds_read_b128 v[118:121], v204 offset:12288
	s_waitcnt lgkmcnt(1)
	v_mfma_f32_32x32x16_bf16 v[98:113], v[114:117], v[130:133], v[98:113]
	s_waitcnt lgkmcnt(0)
	v_mfma_f32_32x32x16_bf16 v[82:97], v[118:121], v[130:133], v[82:97]
	ds_read_b128 v[114:117], v203
	ds_read_b128 v[118:121], v193
	ds_read_b128 v[122:125], v193 offset:1024
	ds_read_b128 v[126:129], v203 offset:12288
	s_waitcnt lgkmcnt(2)
	v_mfma_f32_32x32x16_bf16 v[98:113], v[114:117], v[118:121], v[98:113]
	s_waitcnt lgkmcnt(0)
	v_mfma_f32_32x32x16_bf16 v[82:97], v[126:129], v[118:121], v[82:97]
	ds_read_b128 v[114:117], v202
	ds_read_b128 v[118:121], v202 offset:12288
	s_waitcnt lgkmcnt(1)
	v_mfma_f32_32x32x16_bf16 v[98:113], v[114:117], v[122:125], v[98:113]
	s_waitcnt lgkmcnt(0)
	v_mfma_f32_32x32x16_bf16 v[82:97], v[118:121], v[122:125], v[82:97]
	ds_read_b128 v[114:117], v201
	ds_read_b128 v[118:121], v193 offset:2048
	ds_read_b128 v[122:125], v193 offset:3072
	ds_read_b128 v[126:129], v201 offset:12288
	s_waitcnt lgkmcnt(2)
	v_mfma_f32_32x32x16_bf16 v[98:113], v[114:117], v[118:121], v[98:113]
	s_waitcnt lgkmcnt(0)
	v_mfma_f32_32x32x16_bf16 v[82:97], v[126:129], v[118:121], v[82:97]
	ds_read_b128 v[114:117], v200
	ds_read_b128 v[118:121], v200 offset:12288
	s_waitcnt lgkmcnt(1)
	v_mfma_f32_32x32x16_bf16 v[98:113], v[114:117], v[122:125], v[98:113]
	s_waitcnt lgkmcnt(0)
	v_mfma_f32_32x32x16_bf16 v[82:97], v[118:121], v[122:125], v[82:97]
	s_lshl_b32 s0, s11, 6
	s_or_b32 s1, s0, 63
	s_cmp_le_i32 s1, s96
	s_cbranch_scc1 .LBB0_1445
	v_subrev_u32_e32 v114, s0, v192
	v_cmp_lt_i32_e32 vcc, -1, v114
	s_or_b32 s1, s0, 2
	s_nop 2
	v_cndmask_b32_e32 v98, v185, v98, vcc
	v_cmp_lt_i32_e32 vcc, 31, v114
	v_xad_u32 v114, s0, -1, v192
	s_nop 0
	v_cndmask_b32_e32 v82, v185, v82, vcc
	v_cmp_lt_i32_e32 vcc, -1, v114
	s_nop 1
	v_cndmask_b32_e32 v99, v185, v99, vcc
	v_cmp_lt_i32_e32 vcc, 31, v114
	v_subrev_u32_e32 v114, s1, v192
	s_or_b32 s1, s0, 3
	v_cndmask_b32_e32 v83, v185, v83, vcc
	v_cmp_lt_i32_e32 vcc, -1, v114
	s_nop 1
	v_cndmask_b32_e32 v100, v185, v100, vcc
	v_cmp_lt_i32_e32 vcc, 31, v114
	v_subrev_u32_e32 v114, s1, v192
	s_or_b32 s1, s0, 8
	v_cndmask_b32_e32 v84, v185, v84, vcc
	v_cmp_lt_i32_e32 vcc, -1, v114
	s_nop 1
	v_cndmask_b32_e32 v101, v185, v101, vcc
	v_cmp_lt_i32_e32 vcc, 31, v114
	v_subrev_u32_e32 v114, s1, v192
	s_or_b32 s1, s0, 9
	v_cndmask_b32_e32 v85, v185, v85, vcc
	v_cmp_lt_i32_e32 vcc, -1, v114
	s_nop 1
	v_cndmask_b32_e32 v102, v185, v102, vcc
	v_cmp_lt_i32_e32 vcc, 31, v114
	v_subrev_u32_e32 v114, s1, v192
	s_or_b32 s1, s0, 10
	v_cndmask_b32_e32 v86, v185, v86, vcc
	v_cmp_lt_i32_e32 vcc, -1, v114
	s_nop 1
	v_cndmask_b32_e32 v103, v185, v103, vcc
	v_cmp_lt_i32_e32 vcc, 31, v114
	v_subrev_u32_e32 v114, s1, v192
	s_or_b32 s1, s0, 11
	v_cndmask_b32_e32 v87, v185, v87, vcc
	v_cmp_lt_i32_e32 vcc, -1, v114
	s_nop 1
	v_cndmask_b32_e32 v104, v185, v104, vcc
	v_cmp_lt_i32_e32 vcc, 31, v114
	v_subrev_u32_e32 v114, s1, v192
	s_or_b32 s1, s0, 16
	v_cndmask_b32_e32 v88, v185, v88, vcc
	v_cmp_lt_i32_e32 vcc, -1, v114
	s_nop 1
	v_cndmask_b32_e32 v105, v185, v105, vcc
	v_cmp_lt_i32_e32 vcc, 31, v114
	v_subrev_u32_e32 v114, s1, v192
	s_or_b32 s1, s0, 17
	v_cndmask_b32_e32 v89, v185, v89, vcc
	v_cmp_lt_i32_e32 vcc, -1, v114
	s_nop 1
	v_cndmask_b32_e32 v106, v185, v106, vcc
	v_cmp_lt_i32_e32 vcc, 31, v114
	v_subrev_u32_e32 v114, s1, v192
	s_or_b32 s1, s0, 18
	v_cndmask_b32_e32 v90, v185, v90, vcc
	v_cmp_lt_i32_e32 vcc, -1, v114
	s_nop 1
	v_cndmask_b32_e32 v107, v185, v107, vcc
	v_cmp_lt_i32_e32 vcc, 31, v114
	v_subrev_u32_e32 v114, s1, v192
	s_or_b32 s1, s0, 19
	v_cndmask_b32_e32 v91, v185, v91, vcc
	v_cmp_lt_i32_e32 vcc, -1, v114
	s_nop 1
	v_cndmask_b32_e32 v108, v185, v108, vcc
	v_cmp_lt_i32_e32 vcc, 31, v114
	v_subrev_u32_e32 v114, s1, v192
	s_or_b32 s1, s0, 24
	v_cndmask_b32_e32 v92, v185, v92, vcc
	v_cmp_lt_i32_e32 vcc, -1, v114
	s_nop 1
	v_cndmask_b32_e32 v109, v185, v109, vcc
	v_cmp_lt_i32_e32 vcc, 31, v114
	v_subrev_u32_e32 v114, s1, v192
	s_or_b32 s1, s0, 25
	v_cndmask_b32_e32 v93, v185, v93, vcc
	v_cmp_lt_i32_e32 vcc, -1, v114
	s_nop 1
	v_cndmask_b32_e32 v110, v185, v110, vcc
	v_cmp_lt_i32_e32 vcc, 31, v114
	v_subrev_u32_e32 v114, s1, v192
	s_or_b32 s1, s0, 26
	v_cndmask_b32_e32 v94, v185, v94, vcc
	v_cmp_lt_i32_e32 vcc, -1, v114
	s_or_b32 s0, s0, 27
	s_nop 0
	v_cndmask_b32_e32 v111, v185, v111, vcc
	v_cmp_lt_i32_e32 vcc, 31, v114
	v_subrev_u32_e32 v114, s1, v192
	s_nop 0
	v_cndmask_b32_e32 v95, v185, v95, vcc
	v_cmp_lt_i32_e32 vcc, -1, v114
	s_nop 1
	v_cndmask_b32_e32 v112, v185, v112, vcc
	v_cmp_lt_i32_e32 vcc, 31, v114
	v_subrev_u32_e32 v114, s0, v192
	s_nop 0
	v_cndmask_b32_e32 v96, v185, v96, vcc
	v_cmp_lt_i32_e32 vcc, -1, v114
	s_nop 1
	v_cndmask_b32_e32 v113, v185, v113, vcc
	v_cmp_lt_i32_e32 vcc, 31, v114
	s_nop 1
	v_cndmask_b32_e32 v97, v185, v97, vcc
